# grid barrier: every workgroup polls the cross-XCC generation word directly; per-XCC generation hop removed
# baseline (speedup 1.0000x reference)
.LBB0_1191:
	s_or_b64 exec, exec, s[4:5]
	s_waitcnt vmcnt(0)
	v_readfirstlane_b32 s0, v4
	v_sub_u32_e32 v5, 0, v2
	s_nop 0
	v_add_u32_e32 v4, s0, v3
	v_cvt_f32_u32_e32 v3, v2
	v_rcp_iflag_f32_e32 v3, v3
	s_nop 0
	v_mul_f32_e32 v3, 0x4f7ffffe, v3
	v_cvt_u32_f32_e32 v3, v3
	v_mul_lo_u32 v5, v5, v3
	v_mul_hi_u32 v5, v3, v5
	v_add_u32_e32 v3, v3, v5
	v_mul_hi_u32 v3, v4, v3
	v_mul_lo_u32 v5, v3, v2
	v_sub_u32_e32 v5, v4, v5
	v_cmp_ge_u32_e32 vcc, v5, v2
	v_add_u32_e32 v6, 1, v3
	s_nop 0
	v_cndmask_b32_e32 v3, v3, v6, vcc
	v_sub_u32_e32 v6, v5, v2
	v_cndmask_b32_e32 v5, v5, v6, vcc
	v_cmp_ge_u32_e32 vcc, v5, v2
	v_add_u32_e32 v5, 1, v3
	v_add_u32_e32 v6, 1, v4
	v_cndmask_b32_e32 v3, v3, v5, vcc
	v_mad_u64_u32 v[4:5], s[4:5], v2, v3, v[2:3]
	v_cmp_ne_u32_e32 vcc, v6, v4
	s_and_saveexec_b64 s[4:5], vcc
	s_xor_b64 s[4:5], exec, s[4:5]
	s_cbranch_execz .LBB0_1205
	buffer_inv sc1
	v_readlane_b32 s6, v254, 20
	v_readlane_b32 s7, v254, 21
	s_nop 4
	global_load_dword v0, v1, s[6:7] sc1
	s_waitcnt vmcnt(0)
	v_cmp_eq_u32_e32 vcc, v0, v3
	s_and_saveexec_b64 s[6:7], vcc
	s_cbranch_execz .LBB0_1204
	s_mov_b32 s0, 1
	s_mov_b64 s[8:9], 0
	s_branch .LBB0_1195

.LBB0_1197:
	v_readlane_b32 s12, v254, 20
	v_readlane_b32 s13, v254, 21
	s_add_i32 s0, s0, 1
	s_mov_b64 s[14:15], -1
	s_nop 2
	global_load_dword v0, v1, s[12:13] sc1
	s_waitcnt vmcnt(0)
	v_cmp_ne_u32_e32 vcc, v0, v3
	s_orn2_b64 s[12:13], vcc, exec
	s_branch .LBB0_1194

.LBB0_1223:
	s_bcnt1_i32_b64 s0, s[4:5]
	v_readlane_b32 s4, v254, 16
	v_mov_b32_e32 v0, s0
	v_readlane_b32 s5, v254, 17
	s_getpc_b64 s[98:99]
